# phase 2: half of the workgroups (bit 3 of the id) run the LRU units before the gMLP unit so streaming and compute-bound blocks overlap; on top of 5-tile selected rounds
# speedup vs baseline: 1.0078x; 1.0078x over previous
; __global__ void __launch_bounds__(512, 2) fwd_megakernel(Params PK) {
;     ...
;         const int l = gp >= 9 ? 1 : 0; const int ph = gp == 0 ? 0 : (gp <= 8 ? gp : (gp == 16 ? 8 : gp - 8));
;         if (gp == 0) prologue(lds, P, 0);
;         else if (ph == 1) {
;             { pg8::SchedStd S{64, 75, G, bid, DM, (const bf16_t*)(ws + (l == 0 ? WS_XB : WS_XB2)), (const bf16_t*)(ws + WS_WIN)}; pg8::EpiInProj E{Hh, ws + WS_G8}; pg8::gemm_phase(lds, DM, S, E); }
;             { pg8::SchedStd S{4, 8, G, G - 1 - bid, DM, (const bf16_t*)(ws + WS_MEMB), (const bf16_t*)(ws + WS_WMEM)}; pg8::EpiBf16 E{(bf16_t*)(ws + WS_MKV), DM, 0, nullptr, 0, 0}; pg8::gemm_phase(lds, DM, S, E); }
;         } else if (ph == 2) {
;             for (int u = bid; u < 256; u += G) gmlp_unit(lds, P, l, u);
.LBB0_787:
	s_and_b64 vcc, exec, s[0:1]
	s_cbranch_vccz .LBB0_859
	s_bfe_u32 s46, s2, 0x10003
	s_cmp_eq_u32 s46, 1
	s_cbranch_scc1 .LBB0_804
.Lp2_gmlp:
	v_readlane_b32 s0, v253, 22
	v_readlane_b32 s1, v253, 23
	s_andn2_b64 vcc, exec, s[0:1]
	s_cbranch_vccnz .LBB0_804
	s_add_u32 s8, s68, 0xb181000
	v_readlane_b32 s0, v255, 43
	s_addc_u32 s9, s69, 0
	v_readlane_b32 s1, v255, 44
	s_and_b64 s[0:1], s[0:1], exec
	s_cselect_b32 s0, 0x400, 0
	s_add_u32 s12, s68, 0x28e03000
	s_addc_u32 s13, s69, 0
	s_lshl_b32 s20, s0, 2
	s_mov_b32 s21, s2
	s_branch .LBB0_791

; #define LAS __attribute__((address_space(3)))
; __global__ void __launch_bounds__(512, 2) fwd_megakernel(Params PK) {
;     ...
;             { int cur_n = -1;
;                 for (int u = bid; u < 1024; u += G) { const int n = u & 7;
;                     if (n != cur_n) { __syncthreads(); const bf16_t* WAT = (const bf16_t*)(ws + WS_WAT); LAS bf16_t* wl = (LAS bf16_t*)(lds + 34816);
;                         for (int q = tid; q < 2 * 128 * 16; q += 512) { const int mat = q >> 11, r = (q >> 4) & 127, sg = q & 15;
;                             *(LAS u32x4*)(wl + (mat * 128 + r) * 136 + sg * 8) = *(const u32x4*)(WAT + ((size_t)(mat * 8 + n) * 128 + r) * 128 + sg * 8); }
;                         cur_n = n; __syncthreads(); }
;                     lru_a_unit(lds, P, l, u); } }
.LBB0_804:
	s_cmp_eq_u32 s46, 3
	s_cbranch_scc1 .LBB0_844
	v_readlane_b32 s0, v253, 13
	v_readlane_b32 s1, v253, 14
	s_andn2_b64 vcc, exec, s[0:1]
	s_cbranch_vccnz .LBB0_844
	s_add_u32 s6, s68, 0xb101000
	v_readlane_b32 s0, v255, 43
	s_addc_u32 s7, s69, 0
	v_readlane_b32 s1, v255, 44
	s_and_b64 s[0:1], s[0:1], exec
	s_cselect_b32 s0, 0x400, 0
	s_cselect_b32 s1, 0x1000, 0
	s_add_u32 s20, s68, 0x20e03000
	s_addc_u32 s21, s69, 0
	s_add_u32 s8, s68, 0xb201800
	v_cmp_gt_i32_e32 vcc, s88, v168
	s_addc_u32 s9, s69, 0
	v_lshlrev_b32_e32 v72, 3, v168
	s_mov_b32 s27, -1
	s_lshl_b32 s24, s0, 2
	s_lshl_b32 s25, s1, 2
	s_mov_b32 s26, s2
	s_branch .LBB0_807

; __global__ void __launch_bounds__(512, 2) fwd_megakernel(Params PK) {
;     ...
;                     lru_a_unit(lds, P, l, u); } }
;             { bf16_t* A0 = (bf16_t*)(ws + WS_A0);
.LBB0_844:
	s_cmp_eq_u32 s46, 1
	s_cbranch_scc0 .Lp2_gather
	s_mov_b32 s46, 3
	s_branch .Lp2_gmlp
